# v18 plus attention QK fragment reads software-pipelined 4 deep through 5 rotating register quads
# speedup vs baseline: 1.0044x; 1.0044x over previous
; #define LAS __attribute__((address_space(3)))
; __device__ __forceinline__ void a2_qk(const LAS unsigned char* kb, const bf16x8 (&qf)[6], const f32x16& cneg, f32x16& st0, f32x16& st1) {
;     { const bf16x8 a0 = *(const LAS bf16x8*)(kb), a1 = *(const LAS bf16x8*)(kb + 32 * AT_KROW);
;       st0 = __builtin_amdgcn_mfma_f32_32x32x16_bf16(a0, qf[0], cneg, 0, 0, 0); st1 = __builtin_amdgcn_mfma_f32_32x32x16_bf16(a1, qf[0], cneg, 0, 0, 0); }
; #pragma unroll
;     for (int s = 1; s < 6; ++s) { const bf16x8 a0 = *(const LAS bf16x8*)(kb + s * 32), a1 = *(const LAS bf16x8*)(kb + 32 * AT_KROW + s * 32);
;         st0 = __builtin_amdgcn_mfma_f32_32x32x16_bf16(a0, qf[s], st0, 0, 0, 0); st1 = __builtin_amdgcn_mfma_f32_32x32x16_bf16(a1, qf[s], st1, 0, 0, 0); }
; }
; __device__ __forceinline__ void attn2_unit(bf16_t* Z, const bf16_t* Hb, const float* rc, const float* rs, LAS unsigned char* lds, int b, int h, int qblk) {
;     ...
;         if (2 * kp + 1 <= cw) {
;             f32x16 sa0, sa1, sb0, sb1; bf16x8 pa[4], pb[4];
;             __builtin_amdgcn_s_setprio(1);
;             a2_qk(kb, qf, cneg, sa0, sa1);
.LBB0_824:
	s_andn2_b64 vcc, exec, s[6:7]
	s_cbranch_vccnz .LBB0_833
	s_setprio 1
	v_add_u32_e32 v0, v3, v156
	ds_read_b128 v[4:7], v0
	ds_read_b128 v[8:11], v0 offset:6656
	ds_read_b128 v[12:15], v0 offset:32
	ds_read_b128 v[248:251], v0 offset:6688
	v_mov_b64_e32 v[94:95], v[62:63]
	v_mov_b64_e32 v[92:93], v[60:61]
	v_mov_b64_e32 v[90:91], v[58:59]
	v_mov_b64_e32 v[88:89], v[56:57]
	v_mov_b64_e32 v[86:87], v[54:55]
	v_mov_b64_e32 v[84:85], v[52:53]
	v_mov_b64_e32 v[82:83], v[50:51]
	v_mov_b64_e32 v[80:81], v[48:49]
	s_waitcnt lgkmcnt(3)
	v_mfma_f32_32x32x16_bf16 v[112:127], v[4:7], v[128:131], v[48:63]
	ds_read_b128 v[252:255], v0 offset:64
	s_waitcnt lgkmcnt(3)
	v_mfma_f32_32x32x16_bf16 v[96:111], v[8:11], v[128:131], v[48:63]
	ds_read_b128 v[4:7], v0 offset:6720
	s_waitcnt lgkmcnt(3)
	v_mfma_f32_32x32x16_bf16 v[112:127], v[12:15], v[132:135], v[112:127]
	ds_read_b128 v[8:11], v0 offset:96
	s_waitcnt lgkmcnt(3)
	v_mfma_f32_32x32x16_bf16 v[96:111], v[248:251], v[132:135], v[96:111]
	ds_read_b128 v[12:15], v0 offset:6752
	s_waitcnt lgkmcnt(3)
	v_mfma_f32_32x32x16_bf16 v[112:127], v[252:255], v[136:139], v[112:127]
	ds_read_b128 v[248:251], v0 offset:128
	s_waitcnt lgkmcnt(3)
	v_mfma_f32_32x32x16_bf16 v[96:111], v[4:7], v[136:139], v[96:111]
	ds_read_b128 v[252:255], v0 offset:6784
	s_waitcnt lgkmcnt(3)
	v_mfma_f32_32x32x16_bf16 v[112:127], v[8:11], v[140:143], v[112:127]
	ds_read_b128 v[4:7], v0 offset:160
	s_waitcnt lgkmcnt(3)
	v_mfma_f32_32x32x16_bf16 v[96:111], v[12:15], v[140:143], v[96:111]
	ds_read_b128 v[8:11], v0 offset:13312
	s_waitcnt lgkmcnt(3)
	v_mfma_f32_32x32x16_bf16 v[112:127], v[248:251], v[144:147], v[112:127]
	ds_read_b128 v[12:15], v0 offset:6816
	s_waitcnt lgkmcnt(3)
	v_mfma_f32_32x32x16_bf16 v[96:111], v[252:255], v[144:147], v[96:111]
	ds_read_b128 v[248:251], v0 offset:19968
	s_waitcnt lgkmcnt(3)
	v_mfma_f32_32x32x16_bf16 v[112:127], v[4:7], v[148:151], v[112:127]
	ds_read_b128 v[252:255], v0 offset:13344
	s_waitcnt lgkmcnt(3)
	v_mfma_f32_32x32x16_bf16 v[64:79], v[8:11], v[128:131], v[48:63]
	ds_read_b128 v[4:7], v0 offset:20000
	s_waitcnt lgkmcnt(3)
	v_mfma_f32_32x32x16_bf16 v[96:111], v[12:15], v[148:151], v[96:111]
	ds_read_b128 v[8:11], v0 offset:13376
	s_waitcnt lgkmcnt(3)
	v_mfma_f32_32x32x16_bf16 v[80:95], v[248:251], v[128:131], v[80:95]
	ds_read_b128 v[12:15], v0 offset:20032
	s_waitcnt lgkmcnt(3)
	v_mfma_f32_32x32x16_bf16 v[64:79], v[252:255], v[132:135], v[64:79]
	ds_read_b128 v[248:251], v0 offset:13408
	s_waitcnt lgkmcnt(3)
	v_mfma_f32_32x32x16_bf16 v[80:95], v[4:7], v[132:135], v[80:95]
	ds_read_b128 v[252:255], v0 offset:20064
	s_waitcnt lgkmcnt(3)
	v_mfma_f32_32x32x16_bf16 v[64:79], v[8:11], v[136:139], v[64:79]
	ds_read_b128 v[4:7], v0 offset:13440
	s_waitcnt lgkmcnt(3)
	v_mfma_f32_32x32x16_bf16 v[80:95], v[12:15], v[136:139], v[80:95]
	ds_read_b128 v[8:11], v0 offset:20096
	s_waitcnt lgkmcnt(3)
	v_mfma_f32_32x32x16_bf16 v[64:79], v[248:251], v[140:143], v[64:79]
	ds_read_b128 v[12:15], v0 offset:13472
	s_waitcnt lgkmcnt(3)
	v_mfma_f32_32x32x16_bf16 v[80:95], v[252:255], v[140:143], v[80:95]
	ds_read_b128 v[248:251], v0 offset:20128
	s_waitcnt lgkmcnt(3)
	v_mfma_f32_32x32x16_bf16 v[64:79], v[4:7], v[144:147], v[64:79]
	s_waitcnt lgkmcnt(2)
	v_mfma_f32_32x32x16_bf16 v[80:95], v[8:11], v[144:147], v[80:95]
	s_waitcnt lgkmcnt(1)
	v_mfma_f32_32x32x16_bf16 v[64:79], v[12:15], v[148:151], v[64:79]
	s_waitcnt lgkmcnt(0)
	v_mfma_f32_32x32x16_bf16 v[80:95], v[248:251], v[148:151], v[80:95]
	s_setprio 0
	v_max_f32_e32 v0, v96, v96
	v_max_f32_e32 v3, v112, v112
	v_max_f32_e32 v0, v3, v0
	s_nop 7
	v_max_f32_e32 v3, v80, v80
	v_max_f32_e32 v4, v64, v64
	v_max_f32_e32 v3, v4, v3
	v_max3_f32 v3, v3, v65, v81
	v_max3_f32 v3, v3, v66, v82
	v_max3_f32 v0, v0, v113, v97
	v_max3_f32 v3, v3, v67, v83
	v_max3_f32 v0, v0, v114, v98
	v_max3_f32 v3, v3, v68, v84
	v_max3_f32 v0, v0, v115, v99
	v_max3_f32 v3, v3, v69, v85
	v_max3_f32 v0, v0, v116, v100
	v_max3_f32 v3, v3, v70, v86
	v_max3_f32 v0, v0, v117, v101
	v_max3_f32 v3, v3, v71, v87
	v_max3_f32 v0, v0, v118, v102
	v_max3_f32 v3, v3, v72, v88
	v_max3_f32 v0, v0, v119, v103
	v_max3_f32 v3, v3, v73, v89
	v_max3_f32 v0, v0, v120, v104
	v_max3_f32 v3, v3, v74, v90
	v_max3_f32 v0, v0, v121, v105
	v_max3_f32 v3, v3, v75, v91
	v_max3_f32 v0, v0, v122, v106
	v_max3_f32 v3, v3, v76, v92
	v_max3_f32 v0, v0, v123, v107
	v_max3_f32 v3, v3, v77, v93
	v_max3_f32 v0, v0, v124, v108
	v_max3_f32 v3, v3, v78, v94
	v_max3_f32 v3, v3, v79, v95
	v_max3_f32 v0, v0, v125, v109
	ds_bpermute_b32 v4, v219, v3
	v_max3_f32 v0, v0, v126, v110
	v_max3_f32 v0, v0, v127, v111
	ds_bpermute_b32 v5, v219, v0
	s_cmp_eq_u32 s65, 1
	s_waitcnt lgkmcnt(0)
	v_max_f32_e32 v4, v4, v4
	v_max_f32_e32 v3, v3, v4
	s_cselect_b64 s[34:35], -1, 0
	s_cmp_lg_u32 s65, 1
	v_max3_f32 v3, v0, v5, v3
	s_cbranch_scc0 .LBB0_835
	v_cmp_lt_f32_e32 vcc, s53, v3
	s_mov_b64 s[24:25], 0
	s_mov_b64 s[6:7], 0
	s_cbranch_vccz .LBB0_828
	v_max_f32_e32 v0, v3, v3
	v_max_f32_e32 v0, 0, v0
	s_mov_b64 s[6:7], -1

; #define LAS __attribute__((address_space(3)))
; __device__ __forceinline__ void a2_qk(const LAS unsigned char* kb, const bf16x8 (&qf)[6], const f32x16& cneg, f32x16& st0, f32x16& st1) {
;     { const bf16x8 a0 = *(const LAS bf16x8*)(kb), a1 = *(const LAS bf16x8*)(kb + 32 * AT_KROW);
;       st0 = __builtin_amdgcn_mfma_f32_32x32x16_bf16(a0, qf[0], cneg, 0, 0, 0); st1 = __builtin_amdgcn_mfma_f32_32x32x16_bf16(a1, qf[0], cneg, 0, 0, 0); }
; #pragma unroll
;     for (int s = 1; s < 6; ++s) { const bf16x8 a0 = *(const LAS bf16x8*)(kb + s * 32), a1 = *(const LAS bf16x8*)(kb + 32 * AT_KROW + s * 32);
;         st0 = __builtin_amdgcn_mfma_f32_32x32x16_bf16(a0, qf[s], st0, 0, 0, 0); st1 = __builtin_amdgcn_mfma_f32_32x32x16_bf16(a1, qf[s], st1, 0, 0, 0); }
; }
; __device__ __forceinline__ void attn2_unit(bf16_t* Z, const bf16_t* Hb, const float* rc, const float* rs, LAS unsigned char* lds, int b, int h, int qblk) {
;     ...
;         if (2 * kp + 1 <= cw) {
;             f32x16 sa0, sa1, sb0, sb1; bf16x8 pa[4], pb[4];
;             __builtin_amdgcn_s_setprio(1);
;             a2_qk(kb, qf, cneg, sa0, sa1);
.LBB0_870:
	s_andn2_b64 vcc, exec, s[6:7]
	s_cbranch_vccnz .LBB0_879
	s_setprio 1
	v_add_u32_e32 v0, v3, v156
	ds_read_b128 v[4:7], v0
	ds_read_b128 v[8:11], v0 offset:6656
	ds_read_b128 v[12:15], v0 offset:32
	ds_read_b128 v[248:251], v0 offset:6688
	v_mov_b64_e32 v[94:95], v[62:63]
	v_mov_b64_e32 v[92:93], v[60:61]
	v_mov_b64_e32 v[90:91], v[58:59]
	v_mov_b64_e32 v[88:89], v[56:57]
	v_mov_b64_e32 v[86:87], v[54:55]
	v_mov_b64_e32 v[84:85], v[52:53]
	v_mov_b64_e32 v[82:83], v[50:51]
	v_mov_b64_e32 v[80:81], v[48:49]
	s_waitcnt lgkmcnt(3)
	v_mfma_f32_32x32x16_bf16 v[112:127], v[4:7], v[128:131], v[48:63]
	ds_read_b128 v[252:255], v0 offset:64
	s_waitcnt lgkmcnt(3)
	v_mfma_f32_32x32x16_bf16 v[96:111], v[8:11], v[128:131], v[48:63]
	ds_read_b128 v[4:7], v0 offset:6720
	s_waitcnt lgkmcnt(3)
	v_mfma_f32_32x32x16_bf16 v[112:127], v[12:15], v[132:135], v[112:127]
	ds_read_b128 v[8:11], v0 offset:96
	s_waitcnt lgkmcnt(3)
	v_mfma_f32_32x32x16_bf16 v[96:111], v[248:251], v[132:135], v[96:111]
	ds_read_b128 v[12:15], v0 offset:6752
	s_waitcnt lgkmcnt(3)
	v_mfma_f32_32x32x16_bf16 v[112:127], v[252:255], v[136:139], v[112:127]
	ds_read_b128 v[248:251], v0 offset:128
	s_waitcnt lgkmcnt(3)
	v_mfma_f32_32x32x16_bf16 v[96:111], v[4:7], v[136:139], v[96:111]
	ds_read_b128 v[252:255], v0 offset:6784
	s_waitcnt lgkmcnt(3)
	v_mfma_f32_32x32x16_bf16 v[112:127], v[8:11], v[140:143], v[112:127]
	ds_read_b128 v[4:7], v0 offset:160
	s_waitcnt lgkmcnt(3)
	v_mfma_f32_32x32x16_bf16 v[96:111], v[12:15], v[140:143], v[96:111]
	ds_read_b128 v[8:11], v0 offset:13312
	s_waitcnt lgkmcnt(3)
	v_mfma_f32_32x32x16_bf16 v[112:127], v[248:251], v[144:147], v[112:127]
	ds_read_b128 v[12:15], v0 offset:6816
	s_waitcnt lgkmcnt(3)
	v_mfma_f32_32x32x16_bf16 v[96:111], v[252:255], v[144:147], v[96:111]
	ds_read_b128 v[248:251], v0 offset:19968
	s_waitcnt lgkmcnt(3)
	v_mfma_f32_32x32x16_bf16 v[112:127], v[4:7], v[148:151], v[112:127]
	ds_read_b128 v[252:255], v0 offset:13344
	s_waitcnt lgkmcnt(3)
	v_mfma_f32_32x32x16_bf16 v[64:79], v[8:11], v[128:131], v[48:63]
	ds_read_b128 v[4:7], v0 offset:20000
	s_waitcnt lgkmcnt(3)
	v_mfma_f32_32x32x16_bf16 v[96:111], v[12:15], v[148:151], v[96:111]
	ds_read_b128 v[8:11], v0 offset:13376
	s_waitcnt lgkmcnt(3)
	v_mfma_f32_32x32x16_bf16 v[80:95], v[248:251], v[128:131], v[80:95]
	ds_read_b128 v[12:15], v0 offset:20032
	s_waitcnt lgkmcnt(3)
	v_mfma_f32_32x32x16_bf16 v[64:79], v[252:255], v[132:135], v[64:79]
	ds_read_b128 v[248:251], v0 offset:13408
	s_waitcnt lgkmcnt(3)
	v_mfma_f32_32x32x16_bf16 v[80:95], v[4:7], v[132:135], v[80:95]
	ds_read_b128 v[252:255], v0 offset:20064
	s_waitcnt lgkmcnt(3)
	v_mfma_f32_32x32x16_bf16 v[64:79], v[8:11], v[136:139], v[64:79]
	ds_read_b128 v[4:7], v0 offset:13440
	s_waitcnt lgkmcnt(3)
	v_mfma_f32_32x32x16_bf16 v[80:95], v[12:15], v[136:139], v[80:95]
	ds_read_b128 v[8:11], v0 offset:20096
	s_waitcnt lgkmcnt(3)
	v_mfma_f32_32x32x16_bf16 v[64:79], v[248:251], v[140:143], v[64:79]
	ds_read_b128 v[12:15], v0 offset:13472
	s_waitcnt lgkmcnt(3)
	v_mfma_f32_32x32x16_bf16 v[80:95], v[252:255], v[140:143], v[80:95]
	ds_read_b128 v[248:251], v0 offset:20128
	s_waitcnt lgkmcnt(3)
	v_mfma_f32_32x32x16_bf16 v[64:79], v[4:7], v[144:147], v[64:79]
	s_waitcnt lgkmcnt(2)
	v_mfma_f32_32x32x16_bf16 v[80:95], v[8:11], v[144:147], v[80:95]
	s_waitcnt lgkmcnt(1)
	v_mfma_f32_32x32x16_bf16 v[64:79], v[12:15], v[148:151], v[64:79]
	s_waitcnt lgkmcnt(0)
	v_mfma_f32_32x32x16_bf16 v[80:95], v[248:251], v[148:151], v[80:95]
	s_setprio 0
	v_max_f32_e32 v0, v96, v96
	v_max_f32_e32 v3, v112, v112
	v_max_f32_e32 v0, v3, v0
	s_nop 7
	v_max_f32_e32 v3, v80, v80
	v_max_f32_e32 v4, v64, v64
	v_max_f32_e32 v3, v4, v3
	v_max3_f32 v3, v3, v65, v81
	v_max3_f32 v3, v3, v66, v82
	v_max3_f32 v0, v0, v113, v97
	v_max3_f32 v3, v3, v67, v83
	v_max3_f32 v0, v0, v114, v98
	v_max3_f32 v3, v3, v68, v84
	v_max3_f32 v0, v0, v115, v99
	v_max3_f32 v3, v3, v69, v85
	v_max3_f32 v0, v0, v116, v100
	v_max3_f32 v3, v3, v70, v86
	v_max3_f32 v0, v0, v117, v101
	v_max3_f32 v3, v3, v71, v87
	v_max3_f32 v0, v0, v118, v102
	v_max3_f32 v3, v3, v72, v88
	v_max3_f32 v0, v0, v119, v103
	v_max3_f32 v3, v3, v73, v89
	v_max3_f32 v0, v0, v120, v104
	v_max3_f32 v3, v3, v74, v90
	v_max3_f32 v0, v0, v121, v105
	v_max3_f32 v3, v3, v75, v91
	v_max3_f32 v0, v0, v122, v106
	v_max3_f32 v3, v3, v76, v92
	v_max3_f32 v0, v0, v123, v107
	v_max3_f32 v3, v3, v77, v93
	v_max3_f32 v0, v0, v124, v108
	v_max3_f32 v3, v3, v78, v94
	v_max3_f32 v3, v3, v79, v95
	v_max3_f32 v0, v0, v125, v109
	ds_bpermute_b32 v4, v219, v3
	v_max3_f32 v0, v0, v126, v110
	v_max3_f32 v0, v0, v127, v111
	ds_bpermute_b32 v5, v219, v0
	s_cmp_eq_u32 s35, 1
	s_waitcnt lgkmcnt(0)
	v_max_f32_e32 v4, v4, v4
	v_max_f32_e32 v3, v3, v4
	s_cselect_b64 s[28:29], -1, 0
	s_cmp_lg_u32 s35, 1
	v_max3_f32 v3, v0, v5, v3
	s_cbranch_scc0 .LBB0_881
	v_cmp_lt_f32_e32 vcc, s53, v3
	s_mov_b64 s[24:25], 0
	s_mov_b64 s[6:7], 0
	s_cbranch_vccz .LBB0_874
	v_max_f32_e32 v0, v3, v3
	v_max_f32_e32 v0, 0, v0
	s_mov_b64 s[6:7], -1

; #define LAS __attribute__((address_space(3)))
; __device__ __forceinline__ void a2_qk(const LAS unsigned char* kb, const bf16x8 (&qf)[6], const f32x16& cneg, f32x16& st0, f32x16& st1) {
;     { const bf16x8 a0 = *(const LAS bf16x8*)(kb), a1 = *(const LAS bf16x8*)(kb + 32 * AT_KROW);
;       st0 = __builtin_amdgcn_mfma_f32_32x32x16_bf16(a0, qf[0], cneg, 0, 0, 0); st1 = __builtin_amdgcn_mfma_f32_32x32x16_bf16(a1, qf[0], cneg, 0, 0, 0); }
; #pragma unroll
;     for (int s = 1; s < 6; ++s) { const bf16x8 a0 = *(const LAS bf16x8*)(kb + s * 32), a1 = *(const LAS bf16x8*)(kb + 32 * AT_KROW + s * 32);
;         st0 = __builtin_amdgcn_mfma_f32_32x32x16_bf16(a0, qf[s], st0, 0, 0, 0); st1 = __builtin_amdgcn_mfma_f32_32x32x16_bf16(a1, qf[s], st1, 0, 0, 0); }
; }
; __device__ __forceinline__ void attn2_unit(bf16_t* Z, const bf16_t* Hb, const float* rc, const float* rs, LAS unsigned char* lds, int b, int h, int qblk) {
;     ...
;         if (2 * kp + 1 <= cw) {
;             f32x16 sa0, sa1, sb0, sb1; bf16x8 pa[4], pb[4];
;             __builtin_amdgcn_s_setprio(1);
;             a2_qk(kb, qf, cneg, sa0, sa1);
.LBB0_2235:
	s_andn2_b64 vcc, exec, s[6:7]
	s_cbranch_vccnz .LBB0_2244
	s_setprio 1
	v_add_u32_e32 v0, v3, v156
	ds_read_b128 v[4:7], v0
	ds_read_b128 v[8:11], v0 offset:6656
	ds_read_b128 v[12:15], v0 offset:32
	ds_read_b128 v[248:251], v0 offset:6688
	v_mov_b64_e32 v[94:95], v[62:63]
	v_mov_b64_e32 v[92:93], v[60:61]
	v_mov_b64_e32 v[90:91], v[58:59]
	v_mov_b64_e32 v[88:89], v[56:57]
	v_mov_b64_e32 v[86:87], v[54:55]
	v_mov_b64_e32 v[84:85], v[52:53]
	v_mov_b64_e32 v[82:83], v[50:51]
	v_mov_b64_e32 v[80:81], v[48:49]
	s_waitcnt lgkmcnt(3)
	v_mfma_f32_32x32x16_bf16 v[112:127], v[4:7], v[128:131], v[48:63]
	ds_read_b128 v[252:255], v0 offset:64
	s_waitcnt lgkmcnt(3)
	v_mfma_f32_32x32x16_bf16 v[96:111], v[8:11], v[128:131], v[48:63]
	ds_read_b128 v[4:7], v0 offset:6720
	s_waitcnt lgkmcnt(3)
	v_mfma_f32_32x32x16_bf16 v[112:127], v[12:15], v[132:135], v[112:127]
	ds_read_b128 v[8:11], v0 offset:96
	s_waitcnt lgkmcnt(3)
	v_mfma_f32_32x32x16_bf16 v[96:111], v[248:251], v[132:135], v[96:111]
	ds_read_b128 v[12:15], v0 offset:6752
	s_waitcnt lgkmcnt(3)
	v_mfma_f32_32x32x16_bf16 v[112:127], v[252:255], v[136:139], v[112:127]
	ds_read_b128 v[248:251], v0 offset:128
	s_waitcnt lgkmcnt(3)
	v_mfma_f32_32x32x16_bf16 v[96:111], v[4:7], v[136:139], v[96:111]
	ds_read_b128 v[252:255], v0 offset:6784
	s_waitcnt lgkmcnt(3)
	v_mfma_f32_32x32x16_bf16 v[112:127], v[8:11], v[140:143], v[112:127]
	ds_read_b128 v[4:7], v0 offset:160
	s_waitcnt lgkmcnt(3)
	v_mfma_f32_32x32x16_bf16 v[96:111], v[12:15], v[140:143], v[96:111]
	ds_read_b128 v[8:11], v0 offset:13312
	s_waitcnt lgkmcnt(3)
	v_mfma_f32_32x32x16_bf16 v[112:127], v[248:251], v[144:147], v[112:127]
	ds_read_b128 v[12:15], v0 offset:6816
	s_waitcnt lgkmcnt(3)
	v_mfma_f32_32x32x16_bf16 v[96:111], v[252:255], v[144:147], v[96:111]
	ds_read_b128 v[248:251], v0 offset:19968
	s_waitcnt lgkmcnt(3)
	v_mfma_f32_32x32x16_bf16 v[112:127], v[4:7], v[148:151], v[112:127]
	ds_read_b128 v[252:255], v0 offset:13344
	s_waitcnt lgkmcnt(3)
	v_mfma_f32_32x32x16_bf16 v[64:79], v[8:11], v[128:131], v[48:63]
	ds_read_b128 v[4:7], v0 offset:20000
	s_waitcnt lgkmcnt(3)
	v_mfma_f32_32x32x16_bf16 v[96:111], v[12:15], v[148:151], v[96:111]
	ds_read_b128 v[8:11], v0 offset:13376
	s_waitcnt lgkmcnt(3)
	v_mfma_f32_32x32x16_bf16 v[80:95], v[248:251], v[128:131], v[80:95]
	ds_read_b128 v[12:15], v0 offset:20032
	s_waitcnt lgkmcnt(3)
	v_mfma_f32_32x32x16_bf16 v[64:79], v[252:255], v[132:135], v[64:79]
	ds_read_b128 v[248:251], v0 offset:13408
	s_waitcnt lgkmcnt(3)
	v_mfma_f32_32x32x16_bf16 v[80:95], v[4:7], v[132:135], v[80:95]
	ds_read_b128 v[252:255], v0 offset:20064
	s_waitcnt lgkmcnt(3)
	v_mfma_f32_32x32x16_bf16 v[64:79], v[8:11], v[136:139], v[64:79]
	ds_read_b128 v[4:7], v0 offset:13440
	s_waitcnt lgkmcnt(3)
	v_mfma_f32_32x32x16_bf16 v[80:95], v[12:15], v[136:139], v[80:95]
	ds_read_b128 v[8:11], v0 offset:20096
	s_waitcnt lgkmcnt(3)
	v_mfma_f32_32x32x16_bf16 v[64:79], v[248:251], v[140:143], v[64:79]
	ds_read_b128 v[12:15], v0 offset:13472
	s_waitcnt lgkmcnt(3)
	v_mfma_f32_32x32x16_bf16 v[80:95], v[252:255], v[140:143], v[80:95]
	ds_read_b128 v[248:251], v0 offset:20128
	s_waitcnt lgkmcnt(3)
	v_mfma_f32_32x32x16_bf16 v[64:79], v[4:7], v[144:147], v[64:79]
	s_waitcnt lgkmcnt(2)
	v_mfma_f32_32x32x16_bf16 v[80:95], v[8:11], v[144:147], v[80:95]
	s_waitcnt lgkmcnt(1)
	v_mfma_f32_32x32x16_bf16 v[64:79], v[12:15], v[148:151], v[64:79]
	s_waitcnt lgkmcnt(0)
	v_mfma_f32_32x32x16_bf16 v[80:95], v[248:251], v[148:151], v[80:95]
	s_setprio 0
	v_max_f32_e32 v0, v96, v96
	v_max_f32_e32 v3, v112, v112
	v_max_f32_e32 v0, v3, v0
	s_nop 7
	v_max_f32_e32 v3, v80, v80
	v_max_f32_e32 v4, v64, v64
	v_max_f32_e32 v3, v4, v3
	v_max3_f32 v3, v3, v65, v81
	v_max3_f32 v3, v3, v66, v82
	v_max3_f32 v0, v0, v113, v97
	v_max3_f32 v3, v3, v67, v83
	v_max3_f32 v0, v0, v114, v98
	v_max3_f32 v3, v3, v68, v84
	v_max3_f32 v0, v0, v115, v99
	v_max3_f32 v3, v3, v69, v85
	v_max3_f32 v0, v0, v116, v100
	v_max3_f32 v3, v3, v70, v86
	v_max3_f32 v0, v0, v117, v101
	v_max3_f32 v3, v3, v71, v87
	v_max3_f32 v0, v0, v118, v102
	v_max3_f32 v3, v3, v72, v88
	v_max3_f32 v0, v0, v119, v103
	v_max3_f32 v3, v3, v73, v89
	v_max3_f32 v0, v0, v120, v104
	v_max3_f32 v3, v3, v74, v90
	v_max3_f32 v0, v0, v121, v105
	v_max3_f32 v3, v3, v75, v91
	v_max3_f32 v0, v0, v122, v106
	v_max3_f32 v3, v3, v76, v92
	v_max3_f32 v0, v0, v123, v107
	v_max3_f32 v3, v3, v77, v93
	v_max3_f32 v0, v0, v124, v108
	v_max3_f32 v3, v3, v78, v94
	v_max3_f32 v3, v3, v79, v95
	v_max3_f32 v0, v0, v125, v109
	ds_bpermute_b32 v4, v219, v3
	v_max3_f32 v0, v0, v126, v110
	v_max3_f32 v0, v0, v127, v111
	ds_bpermute_b32 v5, v219, v0
	s_cmp_eq_u32 s47, 1
	s_waitcnt lgkmcnt(0)
	v_max_f32_e32 v4, v4, v4
	v_max_f32_e32 v3, v3, v4
	s_cselect_b64 s[30:31], -1, 0
	s_cmp_lg_u32 s47, 1
	v_max3_f32 v3, v0, v5, v3
	s_cbranch_scc0 .LBB0_2246
	v_cmp_lt_f32_e32 vcc, s41, v3
	s_mov_b64 s[24:25], 0
	s_mov_b64 s[6:7], 0
	s_cbranch_vccz .LBB0_2239
	v_max_f32_e32 v0, v3, v3
	v_max_f32_e32 v0, 0, v0
	s_mov_b64 s[6:7], -1

; #define LAS __attribute__((address_space(3)))
; __device__ __forceinline__ void a2_qk(const LAS unsigned char* kb, const bf16x8 (&qf)[6], const f32x16& cneg, f32x16& st0, f32x16& st1) {
;     { const bf16x8 a0 = *(const LAS bf16x8*)(kb), a1 = *(const LAS bf16x8*)(kb + 32 * AT_KROW);
;       st0 = __builtin_amdgcn_mfma_f32_32x32x16_bf16(a0, qf[0], cneg, 0, 0, 0); st1 = __builtin_amdgcn_mfma_f32_32x32x16_bf16(a1, qf[0], cneg, 0, 0, 0); }
; #pragma unroll
;     for (int s = 1; s < 6; ++s) { const bf16x8 a0 = *(const LAS bf16x8*)(kb + s * 32), a1 = *(const LAS bf16x8*)(kb + 32 * AT_KROW + s * 32);
;         st0 = __builtin_amdgcn_mfma_f32_32x32x16_bf16(a0, qf[s], st0, 0, 0, 0); st1 = __builtin_amdgcn_mfma_f32_32x32x16_bf16(a1, qf[s], st1, 0, 0, 0); }
; }
; __device__ __forceinline__ void attn2_unit(bf16_t* Z, const bf16_t* Hb, const float* rc, const float* rs, LAS unsigned char* lds, int b, int h, int qblk) {
;     ...
;         if (2 * kp + 1 <= cw) {
;             f32x16 sa0, sa1, sb0, sb1; bf16x8 pa[4], pb[4];
;             __builtin_amdgcn_s_setprio(1);
;             a2_qk(kb, qf, cneg, sa0, sa1);
.LBB0_2281:
	s_andn2_b64 vcc, exec, s[6:7]
	s_cbranch_vccnz .LBB0_2290
	s_setprio 1
	v_add_u32_e32 v0, v3, v156
	ds_read_b128 v[4:7], v0
	ds_read_b128 v[8:11], v0 offset:6656
	ds_read_b128 v[12:15], v0 offset:32
	ds_read_b128 v[248:251], v0 offset:6688
	v_mov_b64_e32 v[94:95], v[62:63]
	v_mov_b64_e32 v[92:93], v[60:61]
	v_mov_b64_e32 v[90:91], v[58:59]
	v_mov_b64_e32 v[88:89], v[56:57]
	v_mov_b64_e32 v[86:87], v[54:55]
	v_mov_b64_e32 v[84:85], v[52:53]
	v_mov_b64_e32 v[82:83], v[50:51]
	v_mov_b64_e32 v[80:81], v[48:49]
	s_waitcnt lgkmcnt(3)
	v_mfma_f32_32x32x16_bf16 v[112:127], v[4:7], v[128:131], v[48:63]
	ds_read_b128 v[252:255], v0 offset:64
	s_waitcnt lgkmcnt(3)
	v_mfma_f32_32x32x16_bf16 v[96:111], v[8:11], v[128:131], v[48:63]
	ds_read_b128 v[4:7], v0 offset:6720
	s_waitcnt lgkmcnt(3)
	v_mfma_f32_32x32x16_bf16 v[112:127], v[12:15], v[132:135], v[112:127]
	ds_read_b128 v[8:11], v0 offset:96
	s_waitcnt lgkmcnt(3)
	v_mfma_f32_32x32x16_bf16 v[96:111], v[248:251], v[132:135], v[96:111]
	ds_read_b128 v[12:15], v0 offset:6752
	s_waitcnt lgkmcnt(3)
	v_mfma_f32_32x32x16_bf16 v[112:127], v[252:255], v[136:139], v[112:127]
	ds_read_b128 v[248:251], v0 offset:128
	s_waitcnt lgkmcnt(3)
	v_mfma_f32_32x32x16_bf16 v[96:111], v[4:7], v[136:139], v[96:111]
	ds_read_b128 v[252:255], v0 offset:6784
	s_waitcnt lgkmcnt(3)
	v_mfma_f32_32x32x16_bf16 v[112:127], v[8:11], v[140:143], v[112:127]
	ds_read_b128 v[4:7], v0 offset:160
	s_waitcnt lgkmcnt(3)
	v_mfma_f32_32x32x16_bf16 v[96:111], v[12:15], v[140:143], v[96:111]
	ds_read_b128 v[8:11], v0 offset:13312
	s_waitcnt lgkmcnt(3)
	v_mfma_f32_32x32x16_bf16 v[112:127], v[248:251], v[144:147], v[112:127]
	ds_read_b128 v[12:15], v0 offset:6816
	s_waitcnt lgkmcnt(3)
	v_mfma_f32_32x32x16_bf16 v[96:111], v[252:255], v[144:147], v[96:111]
	ds_read_b128 v[248:251], v0 offset:19968
	s_waitcnt lgkmcnt(3)
	v_mfma_f32_32x32x16_bf16 v[112:127], v[4:7], v[148:151], v[112:127]
	ds_read_b128 v[252:255], v0 offset:13344
	s_waitcnt lgkmcnt(3)
	v_mfma_f32_32x32x16_bf16 v[64:79], v[8:11], v[128:131], v[48:63]
	ds_read_b128 v[4:7], v0 offset:20000
	s_waitcnt lgkmcnt(3)
	v_mfma_f32_32x32x16_bf16 v[96:111], v[12:15], v[148:151], v[96:111]
	ds_read_b128 v[8:11], v0 offset:13376
	s_waitcnt lgkmcnt(3)
	v_mfma_f32_32x32x16_bf16 v[80:95], v[248:251], v[128:131], v[80:95]
	ds_read_b128 v[12:15], v0 offset:20032
	s_waitcnt lgkmcnt(3)
	v_mfma_f32_32x32x16_bf16 v[64:79], v[252:255], v[132:135], v[64:79]
	ds_read_b128 v[248:251], v0 offset:13408
	s_waitcnt lgkmcnt(3)
	v_mfma_f32_32x32x16_bf16 v[80:95], v[4:7], v[132:135], v[80:95]
	ds_read_b128 v[252:255], v0 offset:20064
	s_waitcnt lgkmcnt(3)
	v_mfma_f32_32x32x16_bf16 v[64:79], v[8:11], v[136:139], v[64:79]
	ds_read_b128 v[4:7], v0 offset:13440
	s_waitcnt lgkmcnt(3)
	v_mfma_f32_32x32x16_bf16 v[80:95], v[12:15], v[136:139], v[80:95]
	ds_read_b128 v[8:11], v0 offset:20096
	s_waitcnt lgkmcnt(3)
	v_mfma_f32_32x32x16_bf16 v[64:79], v[248:251], v[140:143], v[64:79]
	ds_read_b128 v[12:15], v0 offset:13472
	s_waitcnt lgkmcnt(3)
	v_mfma_f32_32x32x16_bf16 v[80:95], v[252:255], v[140:143], v[80:95]
	ds_read_b128 v[248:251], v0 offset:20128
	s_waitcnt lgkmcnt(3)
	v_mfma_f32_32x32x16_bf16 v[64:79], v[4:7], v[144:147], v[64:79]
	s_waitcnt lgkmcnt(2)
	v_mfma_f32_32x32x16_bf16 v[80:95], v[8:11], v[144:147], v[80:95]
	s_waitcnt lgkmcnt(1)
	v_mfma_f32_32x32x16_bf16 v[64:79], v[12:15], v[148:151], v[64:79]
	s_waitcnt lgkmcnt(0)
	v_mfma_f32_32x32x16_bf16 v[80:95], v[248:251], v[148:151], v[80:95]
	s_setprio 0
	v_max_f32_e32 v0, v96, v96
	v_max_f32_e32 v3, v112, v112
	v_max_f32_e32 v0, v3, v0
	s_nop 7
	v_max_f32_e32 v3, v80, v80
	v_max_f32_e32 v4, v64, v64
	v_max_f32_e32 v3, v4, v3
	v_max3_f32 v3, v3, v65, v81
	v_max3_f32 v3, v3, v66, v82
	v_max3_f32 v0, v0, v113, v97
	v_max3_f32 v3, v3, v67, v83
	v_max3_f32 v0, v0, v114, v98
	v_max3_f32 v3, v3, v68, v84
	v_max3_f32 v0, v0, v115, v99
	v_max3_f32 v3, v3, v69, v85
	v_max3_f32 v0, v0, v116, v100
	v_max3_f32 v3, v3, v70, v86
	v_max3_f32 v0, v0, v117, v101
	v_max3_f32 v3, v3, v71, v87
	v_max3_f32 v0, v0, v118, v102
	v_max3_f32 v3, v3, v72, v88
	v_max3_f32 v0, v0, v119, v103
	v_max3_f32 v3, v3, v73, v89
	v_max3_f32 v0, v0, v120, v104
	v_max3_f32 v3, v3, v74, v90
	v_max3_f32 v0, v0, v121, v105
	v_max3_f32 v3, v3, v75, v91
	v_max3_f32 v0, v0, v122, v106
	v_max3_f32 v3, v3, v76, v92
	v_max3_f32 v0, v0, v123, v107
	v_max3_f32 v3, v3, v77, v93
	v_max3_f32 v0, v0, v124, v108
	v_max3_f32 v3, v3, v78, v94
	v_max3_f32 v3, v3, v79, v95
	v_max3_f32 v0, v0, v125, v109
	ds_bpermute_b32 v4, v219, v3
	v_max3_f32 v0, v0, v126, v110
	v_max3_f32 v0, v0, v127, v111
	ds_bpermute_b32 v5, v219, v0
	s_cmp_eq_u32 s31, 1
	s_waitcnt lgkmcnt(0)
	v_max_f32_e32 v4, v4, v4
	v_max_f32_e32 v3, v3, v4
	s_cselect_b64 s[26:27], -1, 0
	s_cmp_lg_u32 s31, 1
	v_max3_f32 v3, v0, v5, v3
	s_cbranch_scc0 .LBB0_2292
	v_cmp_lt_f32_e32 vcc, s41, v3
	s_mov_b64 s[24:25], 0
	s_mov_b64 s[6:7], 0
	s_cbranch_vccz .LBB0_2285
	v_max_f32_e32 v0, v3, v3
	v_max_f32_e32 v0, 0, v0
	s_mov_b64 s[6:7], -1

; __global__ void __launch_bounds__(NTHREADS, 2) fwd_kernel(Params p) {
	.amdhsa_kernel _Z10fwd_kernel6Params
		.amdhsa_group_segment_fixed_size 0
		.amdhsa_private_segment_fixed_size 0
		.amdhsa_kernarg_size 512
		.amdhsa_user_sgpr_count 2
		.amdhsa_user_sgpr_dispatch_ptr 0
		.amdhsa_user_sgpr_queue_ptr 0
		.amdhsa_user_sgpr_kernarg_segment_ptr 1
		.amdhsa_user_sgpr_dispatch_id 0
		.amdhsa_user_sgpr_kernarg_preload_length 0
		.amdhsa_user_sgpr_kernarg_preload_offset 0
		.amdhsa_user_sgpr_private_segment_size 0
		.amdhsa_uses_dynamic_stack 0
		.amdhsa_enable_private_segment 0
		.amdhsa_system_sgpr_workgroup_id_x 1
		.amdhsa_system_sgpr_workgroup_id_y 0
		.amdhsa_system_sgpr_workgroup_id_z 0
		.amdhsa_system_sgpr_workgroup_info 0
		.amdhsa_system_vgpr_workitem_id 2
		.amdhsa_next_free_vgpr 256
		.amdhsa_next_free_sgpr 98
		.amdhsa_accum_offset 256
		.amdhsa_reserve_vcc 1
		.amdhsa_float_round_mode_32 0
		.amdhsa_float_round_mode_16_64 0
		.amdhsa_float_denorm_mode_32 3
		.amdhsa_float_denorm_mode_16_64 3
		.amdhsa_dx10_clamp 1
		.amdhsa_ieee_mode 1
		.amdhsa_fp16_overflow 0
		.amdhsa_tg_split 0
		.amdhsa_exception_fp_ieee_invalid_op 0
		.amdhsa_exception_fp_denorm_src 0
		.amdhsa_exception_fp_ieee_div_zero 0
		.amdhsa_exception_fp_ieee_overflow 0
		.amdhsa_exception_fp_ieee_underflow 0
		.amdhsa_exception_fp_ieee_inexact 0
		.amdhsa_exception_int_div_zero 0
	.end_amdhsa_kernel

; __global__ void __launch_bounds__(NTHREADS, 2) fwd_kernel(Params p) {
amdhsa.kernels:
  - .agpr_count:     0
    .args:
      - .offset:         0
        .size:           256
        .value_kind:     by_value
      - .offset:         256
        .size:           4
        .value_kind:     hidden_block_count_x
      - .offset:         260
        .size:           4
        .value_kind:     hidden_block_count_y
      - .offset:         264
        .size:           4
        .value_kind:     hidden_block_count_z
      - .offset:         268
        .size:           2
        .value_kind:     hidden_group_size_x
      - .offset:         270
        .size:           2
        .value_kind:     hidden_group_size_y
      - .offset:         272
        .size:           2
        .value_kind:     hidden_group_size_z
      - .offset:         274
        .size:           2
        .value_kind:     hidden_remainder_x
      - .offset:         276
        .size:           2
        .value_kind:     hidden_remainder_y
      - .offset:         278
        .size:           2
        .value_kind:     hidden_remainder_z
      - .offset:         296
        .size:           8
        .value_kind:     hidden_global_offset_x
      - .offset:         304
        .size:           8
        .value_kind:     hidden_global_offset_y
      - .offset:         312
        .size:           8
        .value_kind:     hidden_global_offset_z
      - .offset:         320
        .size:           2
        .value_kind:     hidden_grid_dims
      - .offset:         344
        .size:           8
        .value_kind:     hidden_multigrid_sync_arg
      - .offset:         376
        .size:           4
        .value_kind:     hidden_dynamic_lds_size
    .group_segment_fixed_size: 0
    .kernarg_segment_align: 8
    .kernarg_segment_size: 512
    .language:       OpenCL C
    .language_version:
      - 2
      - 0
    .max_flat_workgroup_size: 512
    .name:           _Z10fwd_kernel6Params
    .private_segment_fixed_size: 0
    .sgpr_count:     104
    .sgpr_spill_count: 33
    .symbol:         _Z10fwd_kernel6Params.kd
    .uniform_work_group_size: 1
    .uses_dynamic_stack: false
    .vgpr_count:     256
    .vgpr_spill_count: 0
    .wavefront_size: 64
